# v112 + longer back-off (s_sleep 6) in the grid-barrier poll loop to cut same-address polling traffic
# baseline (speedup 1.0000x reference)
; __global__ void __launch_bounds__(256, 2) mega_kernel(Params p) {
;     ...
;     if (ph + 1 < NPHASE) {
;       if (ph == 0) grid.sync();
;       else xcd_barrier(bar, xcc, nloc, nx);
.LBB0_2915:
	s_sleep 6
	global_load_dword v10, v9, s[4:5] offset:32 sc1
	s_waitcnt vmcnt(0)
	v_and_b32_e32 v10, 0xffff0000, v10
	v_cmp_ne_u32_e32 vcc, v10, v8
	s_or_b64 s[6:7], vcc, s[6:7]
	s_andn2_b64 exec, exec, s[6:7]
	s_cbranch_execnz .LBB0_2915
